# hand-scheduled SwiGLU epilogue in P5 (folded rstd scaling, packed adds, no 64-bit address math, no hazard nops)
# speedup vs baseline: 1.0112x; 1.0064x over previous
; __device__ __forceinline__ u32x4 pack8(const f32x4 v0, const f32x4 v1) { u32x4 w; w.x = cvt_pk_bf16(v0[0], v0[1]); w.y = cvt_pk_bf16(v0[2], v0[3]); w.z = cvt_pk_bf16(v1[0], v1[1]); w.w = cvt_pk_bf16(v1[2], v1[3]); return w; }
; __device__ __forceinline__ float sigm(float v) { return __builtin_amdgcn_rcpf(1.0f + __expf(-v)); }
;     __device__ __forceinline__ void operator()(const f32x4 (&acc)[2][2][4][2], const Unit& u, int wr, int wc, int fr_in, int fq_in) const {
;     ...
; #pragma unroll
;         for (int ai = 0; ai < 2; ++ai)
; #pragma unroll
;             for (int m = 0; m < 4; ++m) {
;                 f32x4 o[2];
; #pragma unroll
;                 for (int n = 0; n < 2; ++n) {
;                     const f32x4 g = acc[ai][0][m][n] * rstd[ai][m], up = acc[ai][1][m][n] * rstd[ai][m];
; #pragma unroll
;                     for (int e = 0; e < 4; ++e) o[n][e] = g[e] * sigm(g[e]) * up[e];
;                 }
;                 *(u32x4*)(act + (size_t)(row0 + ai * HALF + m * 16) * ldc + u.pn * HALF + wc * 32 + 8 * fq) = pack8(o[0], o[1]);
.LBB0_589:
	s_movk_i32 s4, 0x1600
	s_lshl_b32 s40, s24, 8
	v_mul_u32_u24_e32 v131, 0x1600, v182
	s_add_u32 s40, s6, s40
	s_addc_u32 s41, s7, 0
	v_mov_b32_e32 v178, 1.0
	v_mov_b32_e32 v179, 1.0
	s_add_u32 s40, s40, s90
	s_addc_u32 s41, s41, s91
	v_lshl_add_u32 v131, v187, 4, v131
	v_mul_f32_e32 v156, 0xbfb8aa3b, v184
	v_mul_f32_e32 v172, v184, v184
	v_pk_mul_f32 v[158:159], v[126:127], v[156:157] op_sel_hi:[1,0]
	v_pk_mul_f32 v[160:161], v[128:129], v[156:157] op_sel_hi:[1,0]
	v_pk_mul_f32 v[162:163], v[118:119], v[156:157] op_sel_hi:[1,0]
	v_pk_mul_f32 v[166:167], v[120:121], v[156:157] op_sel_hi:[1,0]
	v_exp_f32_e32 v158, v158
	v_exp_f32_e32 v159, v159
	v_pk_mul_f32 v[122:123], v[126:127], v[122:123]
	v_exp_f32_e32 v160, v160
	v_exp_f32_e32 v161, v161
	v_pk_mul_f32 v[124:125], v[128:129], v[124:125]
	v_exp_f32_e32 v162, v162
	v_exp_f32_e32 v163, v163
	v_pk_mul_f32 v[114:115], v[118:119], v[114:115]
	v_exp_f32_e32 v166, v166
	v_exp_f32_e32 v167, v167
	v_pk_mul_f32 v[116:117], v[120:121], v[116:117]
	v_pk_add_f32 v[158:159], v[158:159], v[178:179]
	v_pk_add_f32 v[160:161], v[160:161], v[178:179]
	v_pk_add_f32 v[162:163], v[162:163], v[178:179]
	v_pk_add_f32 v[166:167], v[166:167], v[178:179]
	v_rcp_f32_e32 v158, v158
	v_rcp_f32_e32 v159, v159
	v_pk_mul_f32 v[122:123], v[122:123], v[172:173] op_sel_hi:[1,0]
	v_rcp_f32_e32 v160, v160
	v_rcp_f32_e32 v161, v161
	v_pk_mul_f32 v[124:125], v[124:125], v[172:173] op_sel_hi:[1,0]
	v_rcp_f32_e32 v162, v162
	v_rcp_f32_e32 v163, v163
	v_pk_mul_f32 v[114:115], v[114:115], v[172:173] op_sel_hi:[1,0]
	v_rcp_f32_e32 v166, v166
	v_rcp_f32_e32 v167, v167
	v_pk_mul_f32 v[116:117], v[116:117], v[172:173] op_sel_hi:[1,0]
	v_mul_f32_e32 v156, 0xbfb8aa3b, v180
	v_mul_f32_e32 v172, v180, v180
	v_pk_mul_f32 v[122:123], v[122:123], v[158:159]
	v_pk_mul_f32 v[124:125], v[124:125], v[160:161]
	v_pk_mul_f32 v[114:115], v[114:115], v[162:163]
	v_pk_mul_f32 v[116:117], v[116:117], v[166:167]
	v_cvt_pk_bf16_f32 v132, v122, v123
	v_cvt_pk_bf16_f32 v133, v124, v125
	v_cvt_pk_bf16_f32 v134, v114, v115
	v_cvt_pk_bf16_f32 v135, v116, v117
	s_nop 0
	global_store_dwordx4 v131, v[132:135], s[40:41]
	v_add_u32_e32 v131, 0x16000, v131
	v_pk_mul_f32 v[158:159], v[110:111], v[156:157] op_sel_hi:[1,0]
	v_pk_mul_f32 v[160:161], v[112:113], v[156:157] op_sel_hi:[1,0]
	v_pk_mul_f32 v[162:163], v[102:103], v[156:157] op_sel_hi:[1,0]
	v_pk_mul_f32 v[166:167], v[104:105], v[156:157] op_sel_hi:[1,0]
	v_exp_f32_e32 v158, v158
	v_exp_f32_e32 v159, v159
	v_pk_mul_f32 v[106:107], v[110:111], v[106:107]
	v_exp_f32_e32 v160, v160
	v_exp_f32_e32 v161, v161
	v_pk_mul_f32 v[108:109], v[112:113], v[108:109]
	v_exp_f32_e32 v162, v162
	v_exp_f32_e32 v163, v163
	v_pk_mul_f32 v[98:99], v[102:103], v[98:99]
	v_exp_f32_e32 v166, v166
	v_exp_f32_e32 v167, v167
	v_pk_mul_f32 v[100:101], v[104:105], v[100:101]
	v_pk_add_f32 v[158:159], v[158:159], v[178:179]
	v_pk_add_f32 v[160:161], v[160:161], v[178:179]
	v_pk_add_f32 v[162:163], v[162:163], v[178:179]
	v_pk_add_f32 v[166:167], v[166:167], v[178:179]
	v_rcp_f32_e32 v158, v158
	v_rcp_f32_e32 v159, v159
	v_pk_mul_f32 v[106:107], v[106:107], v[172:173] op_sel_hi:[1,0]
	v_rcp_f32_e32 v160, v160
	v_rcp_f32_e32 v161, v161
	v_pk_mul_f32 v[108:109], v[108:109], v[172:173] op_sel_hi:[1,0]
	v_rcp_f32_e32 v162, v162
	v_rcp_f32_e32 v163, v163
	v_pk_mul_f32 v[98:99], v[98:99], v[172:173] op_sel_hi:[1,0]
	v_rcp_f32_e32 v166, v166
	v_rcp_f32_e32 v167, v167
	v_pk_mul_f32 v[100:101], v[100:101], v[172:173] op_sel_hi:[1,0]
	v_mul_f32_e32 v156, 0xbfb8aa3b, v176
	v_mul_f32_e32 v172, v176, v176
	v_pk_mul_f32 v[106:107], v[106:107], v[158:159]
	v_pk_mul_f32 v[108:109], v[108:109], v[160:161]
	v_pk_mul_f32 v[98:99], v[98:99], v[162:163]
	v_pk_mul_f32 v[100:101], v[100:101], v[166:167]
	v_cvt_pk_bf16_f32 v132, v106, v107
	v_cvt_pk_bf16_f32 v133, v108, v109
	v_cvt_pk_bf16_f32 v134, v98, v99
	v_cvt_pk_bf16_f32 v135, v100, v101
	s_nop 0
	global_store_dwordx4 v131, v[132:135], s[40:41]
	v_add_u32_e32 v131, 0x16000, v131
	v_pk_mul_f32 v[158:159], v[94:95], v[156:157] op_sel_hi:[1,0]
	v_pk_mul_f32 v[160:161], v[96:97], v[156:157] op_sel_hi:[1,0]
	v_pk_mul_f32 v[162:163], v[86:87], v[156:157] op_sel_hi:[1,0]
	v_pk_mul_f32 v[166:167], v[88:89], v[156:157] op_sel_hi:[1,0]
	v_exp_f32_e32 v158, v158
	v_exp_f32_e32 v159, v159
	v_pk_mul_f32 v[90:91], v[94:95], v[90:91]
	v_exp_f32_e32 v160, v160
	v_exp_f32_e32 v161, v161
	v_pk_mul_f32 v[92:93], v[96:97], v[92:93]
	v_exp_f32_e32 v162, v162
	v_exp_f32_e32 v163, v163
	v_pk_mul_f32 v[82:83], v[86:87], v[82:83]
	v_exp_f32_e32 v166, v166
	v_exp_f32_e32 v167, v167
	v_pk_mul_f32 v[84:85], v[88:89], v[84:85]
	v_pk_add_f32 v[158:159], v[158:159], v[178:179]
	v_pk_add_f32 v[160:161], v[160:161], v[178:179]
	v_pk_add_f32 v[162:163], v[162:163], v[178:179]
	v_pk_add_f32 v[166:167], v[166:167], v[178:179]
	v_rcp_f32_e32 v158, v158
	v_rcp_f32_e32 v159, v159
	v_pk_mul_f32 v[90:91], v[90:91], v[172:173] op_sel_hi:[1,0]
	v_rcp_f32_e32 v160, v160
	v_rcp_f32_e32 v161, v161
	v_pk_mul_f32 v[92:93], v[92:93], v[172:173] op_sel_hi:[1,0]
	v_rcp_f32_e32 v162, v162
	v_rcp_f32_e32 v163, v163
	v_pk_mul_f32 v[82:83], v[82:83], v[172:173] op_sel_hi:[1,0]
	v_rcp_f32_e32 v166, v166
	v_rcp_f32_e32 v167, v167
	v_pk_mul_f32 v[84:85], v[84:85], v[172:173] op_sel_hi:[1,0]
	v_mul_f32_e32 v156, 0xbfb8aa3b, v174
	v_mul_f32_e32 v172, v174, v174
	v_pk_mul_f32 v[90:91], v[90:91], v[158:159]
	v_pk_mul_f32 v[92:93], v[92:93], v[160:161]
	v_pk_mul_f32 v[82:83], v[82:83], v[162:163]
	v_pk_mul_f32 v[84:85], v[84:85], v[166:167]
	v_cvt_pk_bf16_f32 v132, v90, v91
	v_cvt_pk_bf16_f32 v133, v92, v93
	v_cvt_pk_bf16_f32 v134, v82, v83
; __device__ __forceinline__ u32x4 pack8(const f32x4 v0, const f32x4 v1) { u32x4 w; w.x = cvt_pk_bf16(v0[0], v0[1]); w.y = cvt_pk_bf16(v0[2], v0[3]); w.z = cvt_pk_bf16(v1[0], v1[1]); w.w = cvt_pk_bf16(v1[2], v1[3]); return w; }
; __device__ __forceinline__ float sigm(float v) { return __builtin_amdgcn_rcpf(1.0f + __expf(-v)); }
;     __device__ __forceinline__ void operator()(const f32x4 (&acc)[2][2][4][2], const Unit& u, int wr, int wc, int fr_in, int fq_in) const {
;     ...
; #pragma unroll
;         for (int ai = 0; ai < 2; ++ai)
; #pragma unroll
;             for (int m = 0; m < 4; ++m) {
;                 f32x4 o[2];
; #pragma unroll
;                 for (int n = 0; n < 2; ++n) {
;                     const f32x4 g = acc[ai][0][m][n] * rstd[ai][m], up = acc[ai][1][m][n] * rstd[ai][m];
; #pragma unroll
;                     for (int e = 0; e < 4; ++e) o[n][e] = g[e] * sigm(g[e]) * up[e];
;                 }
;                 *(u32x4*)(act + (size_t)(row0 + ai * HALF + m * 16) * ldc + u.pn * HALF + wc * 32 + 8 * fq) = pack8(o[0], o[1]);
	v_cvt_pk_bf16_f32 v135, v84, v85
	s_nop 0
	global_store_dwordx4 v131, v[132:135], s[40:41]
	v_add_u32_e32 v131, 0x16000, v131
	v_pk_mul_f32 v[158:159], v[78:79], v[156:157] op_sel_hi:[1,0]
	v_pk_mul_f32 v[160:161], v[80:81], v[156:157] op_sel_hi:[1,0]
	v_pk_mul_f32 v[162:163], v[70:71], v[156:157] op_sel_hi:[1,0]
	v_pk_mul_f32 v[166:167], v[72:73], v[156:157] op_sel_hi:[1,0]
	v_exp_f32_e32 v158, v158
	v_exp_f32_e32 v159, v159
	v_pk_mul_f32 v[74:75], v[78:79], v[74:75]
	v_exp_f32_e32 v160, v160
	v_exp_f32_e32 v161, v161
	v_pk_mul_f32 v[76:77], v[80:81], v[76:77]
	v_exp_f32_e32 v162, v162
	v_exp_f32_e32 v163, v163
	v_pk_mul_f32 v[66:67], v[70:71], v[66:67]
	v_exp_f32_e32 v166, v166
	v_exp_f32_e32 v167, v167
	v_pk_mul_f32 v[68:69], v[72:73], v[68:69]
	v_pk_add_f32 v[158:159], v[158:159], v[178:179]
	v_pk_add_f32 v[160:161], v[160:161], v[178:179]
	v_pk_add_f32 v[162:163], v[162:163], v[178:179]
	v_pk_add_f32 v[166:167], v[166:167], v[178:179]
	v_rcp_f32_e32 v158, v158
	v_rcp_f32_e32 v159, v159
	v_pk_mul_f32 v[74:75], v[74:75], v[172:173] op_sel_hi:[1,0]
	v_rcp_f32_e32 v160, v160
	v_rcp_f32_e32 v161, v161
	v_pk_mul_f32 v[76:77], v[76:77], v[172:173] op_sel_hi:[1,0]
	v_rcp_f32_e32 v162, v162
	v_rcp_f32_e32 v163, v163
	v_pk_mul_f32 v[66:67], v[66:67], v[172:173] op_sel_hi:[1,0]
	v_rcp_f32_e32 v166, v166
	v_rcp_f32_e32 v167, v167
	v_pk_mul_f32 v[68:69], v[68:69], v[172:173] op_sel_hi:[1,0]
	v_mul_f32_e32 v156, 0xbfb8aa3b, v170
	v_mul_f32_e32 v172, v170, v170
	v_pk_mul_f32 v[74:75], v[74:75], v[158:159]
	v_pk_mul_f32 v[76:77], v[76:77], v[160:161]
	v_pk_mul_f32 v[66:67], v[66:67], v[162:163]
	v_pk_mul_f32 v[68:69], v[68:69], v[166:167]
	v_cvt_pk_bf16_f32 v132, v74, v75
	v_cvt_pk_bf16_f32 v133, v76, v77
	v_cvt_pk_bf16_f32 v134, v66, v67
	v_cvt_pk_bf16_f32 v135, v68, v69
	s_nop 0
	global_store_dwordx4 v131, v[132:135], s[40:41]
	v_add_u32_e32 v131, 0x6e000, v131
	v_pk_mul_f32 v[158:159], v[62:63], v[156:157] op_sel_hi:[1,0]
	v_pk_mul_f32 v[160:161], v[64:65], v[156:157] op_sel_hi:[1,0]
	v_pk_mul_f32 v[162:163], v[54:55], v[156:157] op_sel_hi:[1,0]
	v_pk_mul_f32 v[166:167], v[56:57], v[156:157] op_sel_hi:[1,0]
	v_exp_f32_e32 v158, v158
	v_exp_f32_e32 v159, v159
	v_pk_mul_f32 v[58:59], v[62:63], v[58:59]
	v_exp_f32_e32 v160, v160
	v_exp_f32_e32 v161, v161
	v_pk_mul_f32 v[60:61], v[64:65], v[60:61]
	v_exp_f32_e32 v162, v162
	v_exp_f32_e32 v163, v163
	v_pk_mul_f32 v[50:51], v[54:55], v[50:51]
	v_exp_f32_e32 v166, v166
	v_exp_f32_e32 v167, v167
	v_pk_mul_f32 v[52:53], v[56:57], v[52:53]
	v_pk_add_f32 v[158:159], v[158:159], v[178:179]
	v_pk_add_f32 v[160:161], v[160:161], v[178:179]
	v_pk_add_f32 v[162:163], v[162:163], v[178:179]
	v_pk_add_f32 v[166:167], v[166:167], v[178:179]
	v_rcp_f32_e32 v158, v158
	v_rcp_f32_e32 v159, v159
	v_pk_mul_f32 v[58:59], v[58:59], v[172:173] op_sel_hi:[1,0]
	v_rcp_f32_e32 v160, v160
	v_rcp_f32_e32 v161, v161
	v_pk_mul_f32 v[60:61], v[60:61], v[172:173] op_sel_hi:[1,0]
	v_rcp_f32_e32 v162, v162
	v_rcp_f32_e32 v163, v163
	v_pk_mul_f32 v[50:51], v[50:51], v[172:173] op_sel_hi:[1,0]
	v_rcp_f32_e32 v166, v166
	v_rcp_f32_e32 v167, v167
	v_pk_mul_f32 v[52:53], v[52:53], v[172:173] op_sel_hi:[1,0]
	v_mul_f32_e32 v156, 0xbfb8aa3b, v168
	v_mul_f32_e32 v172, v168, v168
	v_pk_mul_f32 v[58:59], v[58:59], v[158:159]
	v_pk_mul_f32 v[60:61], v[60:61], v[160:161]
	v_pk_mul_f32 v[50:51], v[50:51], v[162:163]
	v_pk_mul_f32 v[52:53], v[52:53], v[166:167]
	v_cvt_pk_bf16_f32 v132, v58, v59
	v_cvt_pk_bf16_f32 v133, v60, v61
	v_cvt_pk_bf16_f32 v134, v50, v51
	v_cvt_pk_bf16_f32 v135, v52, v53
	s_nop 0
	global_store_dwordx4 v131, v[132:135], s[40:41]
	v_add_u32_e32 v131, 0x16000, v131
	v_pk_mul_f32 v[158:159], v[46:47], v[156:157] op_sel_hi:[1,0]
	v_pk_mul_f32 v[160:161], v[48:49], v[156:157] op_sel_hi:[1,0]
	v_pk_mul_f32 v[162:163], v[38:39], v[156:157] op_sel_hi:[1,0]
	v_pk_mul_f32 v[166:167], v[40:41], v[156:157] op_sel_hi:[1,0]
	v_exp_f32_e32 v158, v158
	v_exp_f32_e32 v159, v159
	v_pk_mul_f32 v[42:43], v[46:47], v[42:43]
	v_exp_f32_e32 v160, v160
	v_exp_f32_e32 v161, v161
	v_pk_mul_f32 v[44:45], v[48:49], v[44:45]
	v_exp_f32_e32 v162, v162
	v_exp_f32_e32 v163, v163
	v_pk_mul_f32 v[34:35], v[38:39], v[34:35]
	v_exp_f32_e32 v166, v166
	v_exp_f32_e32 v167, v167
	v_pk_mul_f32 v[36:37], v[40:41], v[36:37]
	v_pk_add_f32 v[158:159], v[158:159], v[178:179]
	v_pk_add_f32 v[160:161], v[160:161], v[178:179]
	v_pk_add_f32 v[162:163], v[162:163], v[178:179]
	v_pk_add_f32 v[166:167], v[166:167], v[178:179]
; __device__ __forceinline__ u32x4 pack8(const f32x4 v0, const f32x4 v1) { u32x4 w; w.x = cvt_pk_bf16(v0[0], v0[1]); w.y = cvt_pk_bf16(v0[2], v0[3]); w.z = cvt_pk_bf16(v1[0], v1[1]); w.w = cvt_pk_bf16(v1[2], v1[3]); return w; }
; __device__ __forceinline__ float sigm(float v) { return __builtin_amdgcn_rcpf(1.0f + __expf(-v)); }
;     __device__ __forceinline__ void operator()(const f32x4 (&acc)[2][2][4][2], const Unit& u, int wr, int wc, int fr_in, int fq_in) const {
;     ...
; #pragma unroll
;         for (int ai = 0; ai < 2; ++ai)
; #pragma unroll
;             for (int m = 0; m < 4; ++m) {
;                 f32x4 o[2];
; #pragma unroll
;                 for (int n = 0; n < 2; ++n) {
;                     const f32x4 g = acc[ai][0][m][n] * rstd[ai][m], up = acc[ai][1][m][n] * rstd[ai][m];
; #pragma unroll
;                     for (int e = 0; e < 4; ++e) o[n][e] = g[e] * sigm(g[e]) * up[e];
;                 }
;                 *(u32x4*)(act + (size_t)(row0 + ai * HALF + m * 16) * ldc + u.pn * HALF + wc * 32 + 8 * fq) = pack8(o[0], o[1]);
	v_rcp_f32_e32 v158, v158
	v_rcp_f32_e32 v159, v159
	v_pk_mul_f32 v[42:43], v[42:43], v[172:173] op_sel_hi:[1,0]
	v_rcp_f32_e32 v160, v160
	v_rcp_f32_e32 v161, v161
	v_pk_mul_f32 v[44:45], v[44:45], v[172:173] op_sel_hi:[1,0]
	v_rcp_f32_e32 v162, v162
	v_rcp_f32_e32 v163, v163
	v_pk_mul_f32 v[34:35], v[34:35], v[172:173] op_sel_hi:[1,0]
	v_rcp_f32_e32 v166, v166
	v_rcp_f32_e32 v167, v167
	v_pk_mul_f32 v[36:37], v[36:37], v[172:173] op_sel_hi:[1,0]
	v_mul_f32_e32 v156, 0xbfb8aa3b, v164
	v_mul_f32_e32 v172, v164, v164
	v_pk_mul_f32 v[42:43], v[42:43], v[158:159]
	v_pk_mul_f32 v[44:45], v[44:45], v[160:161]
	v_pk_mul_f32 v[34:35], v[34:35], v[162:163]
	v_pk_mul_f32 v[36:37], v[36:37], v[166:167]
	v_cvt_pk_bf16_f32 v132, v42, v43
	v_cvt_pk_bf16_f32 v133, v44, v45
	v_cvt_pk_bf16_f32 v134, v34, v35
	v_cvt_pk_bf16_f32 v135, v36, v37
	s_nop 0
	global_store_dwordx4 v131, v[132:135], s[40:41]
	v_add_u32_e32 v131, 0x16000, v131
	v_pk_mul_f32 v[158:159], v[30:31], v[156:157] op_sel_hi:[1,0]
	v_pk_mul_f32 v[160:161], v[32:33], v[156:157] op_sel_hi:[1,0]
	v_pk_mul_f32 v[162:163], v[22:23], v[156:157] op_sel_hi:[1,0]
	v_pk_mul_f32 v[166:167], v[24:25], v[156:157] op_sel_hi:[1,0]
	v_exp_f32_e32 v158, v158
	v_exp_f32_e32 v159, v159
	v_pk_mul_f32 v[26:27], v[30:31], v[26:27]
	v_exp_f32_e32 v160, v160
	v_exp_f32_e32 v161, v161
	v_pk_mul_f32 v[28:29], v[32:33], v[28:29]
	v_exp_f32_e32 v162, v162
	v_exp_f32_e32 v163, v163
	v_pk_mul_f32 v[18:19], v[22:23], v[18:19]
	v_exp_f32_e32 v166, v166
	v_exp_f32_e32 v167, v167
	v_pk_mul_f32 v[20:21], v[24:25], v[20:21]
	v_pk_add_f32 v[158:159], v[158:159], v[178:179]
	v_pk_add_f32 v[160:161], v[160:161], v[178:179]
	v_pk_add_f32 v[162:163], v[162:163], v[178:179]
	v_pk_add_f32 v[166:167], v[166:167], v[178:179]
	v_rcp_f32_e32 v158, v158
	v_rcp_f32_e32 v159, v159
	v_pk_mul_f32 v[26:27], v[26:27], v[172:173] op_sel_hi:[1,0]
	v_rcp_f32_e32 v160, v160
	v_rcp_f32_e32 v161, v161
	v_pk_mul_f32 v[28:29], v[28:29], v[172:173] op_sel_hi:[1,0]
	v_rcp_f32_e32 v162, v162
	v_rcp_f32_e32 v163, v163
	v_pk_mul_f32 v[18:19], v[18:19], v[172:173] op_sel_hi:[1,0]
	v_rcp_f32_e32 v166, v166
	v_rcp_f32_e32 v167, v167
	v_pk_mul_f32 v[20:21], v[20:21], v[172:173] op_sel_hi:[1,0]
	v_mul_f32_e32 v156, 0xbfb8aa3b, v130
	v_mul_f32_e32 v172, v130, v130
	v_pk_mul_f32 v[26:27], v[26:27], v[158:159]
	v_pk_mul_f32 v[28:29], v[28:29], v[160:161]
	v_pk_mul_f32 v[18:19], v[18:19], v[162:163]
	v_pk_mul_f32 v[20:21], v[20:21], v[166:167]
	v_cvt_pk_bf16_f32 v132, v26, v27
	v_cvt_pk_bf16_f32 v133, v28, v29
	v_cvt_pk_bf16_f32 v134, v18, v19
	v_cvt_pk_bf16_f32 v135, v20, v21
	s_nop 0
	global_store_dwordx4 v131, v[132:135], s[40:41]
	v_add_u32_e32 v131, 0x16000, v131
	v_pk_mul_f32 v[158:159], v[14:15], v[156:157] op_sel_hi:[1,0]
	v_pk_mul_f32 v[160:161], v[16:17], v[156:157] op_sel_hi:[1,0]
	v_pk_mul_f32 v[162:163], v[6:7], v[156:157] op_sel_hi:[1,0]
	v_pk_mul_f32 v[166:167], v[8:9], v[156:157] op_sel_hi:[1,0]
	v_exp_f32_e32 v158, v158
	v_exp_f32_e32 v159, v159
	v_pk_mul_f32 v[10:11], v[14:15], v[10:11]
	v_exp_f32_e32 v160, v160
	v_exp_f32_e32 v161, v161
	v_pk_mul_f32 v[12:13], v[16:17], v[12:13]
	v_exp_f32_e32 v162, v162
	v_exp_f32_e32 v163, v163
	v_pk_mul_f32 v[2:3], v[6:7], v[2:3]
	v_exp_f32_e32 v166, v166
	v_exp_f32_e32 v167, v167
	v_pk_mul_f32 v[4:5], v[8:9], v[4:5]
	v_pk_add_f32 v[158:159], v[158:159], v[178:179]
	v_pk_add_f32 v[160:161], v[160:161], v[178:179]
	v_pk_add_f32 v[162:163], v[162:163], v[178:179]
	v_pk_add_f32 v[166:167], v[166:167], v[178:179]
	v_rcp_f32_e32 v158, v158
	v_rcp_f32_e32 v159, v159
	v_pk_mul_f32 v[10:11], v[10:11], v[172:173] op_sel_hi:[1,0]
	v_rcp_f32_e32 v160, v160
	v_rcp_f32_e32 v161, v161
	v_pk_mul_f32 v[12:13], v[12:13], v[172:173] op_sel_hi:[1,0]
	v_rcp_f32_e32 v162, v162
	v_rcp_f32_e32 v163, v163
	v_pk_mul_f32 v[2:3], v[2:3], v[172:173] op_sel_hi:[1,0]
	v_rcp_f32_e32 v166, v166
	v_rcp_f32_e32 v167, v167
	v_pk_mul_f32 v[4:5], v[4:5], v[172:173] op_sel_hi:[1,0]
	s_nop 0
	v_pk_mul_f32 v[10:11], v[10:11], v[158:159]
	v_pk_mul_f32 v[12:13], v[12:13], v[160:161]
	v_pk_mul_f32 v[2:3], v[2:3], v[162:163]
	v_pk_mul_f32 v[4:5], v[4:5], v[166:167]
	v_cvt_pk_bf16_f32 v132, v10, v11
	v_cvt_pk_bf16_f32 v133, v12, v13
	v_cvt_pk_bf16_f32 v134, v2, v3
	v_cvt_pk_bf16_f32 v135, v4, v5
	s_nop 0
	global_store_dwordx4 v131, v[132:135], s[40:41]
	s_andn2_b64 vcc, exec, s[38:39]
	s_nop 4
	s_mov_b64 s[40:41], -1
	s_cbranch_vccnz .LBB0_578
	s_andn2_b64 vcc, exec, s[2:3]
	s_cbranch_vccnz .LBB0_577
	s_barrier
	s_branch .LBB0_577
